# retention scan state update hand-scheduled: V'^T fragments read once, K^T fragments prefetched 4 tiles ahead in a register ring, MFMA order and arithmetic unchanged
# speedup vs baseline: 1.0883x; 1.0034x over previous
; #define RET_STORE_K(src) do { \
;         _Pragma("unroll") for (int i = 0; i < 4; ++i) { const int id = tid + 512 * i, s_ = id >> 5, dc = id & 31; *(LAS u32x4*)(L + OFF_K + s_ * QP + dc * 16) = src[i]; } } while (0)
; __device__ __forceinline__ void phase_ret_scan(KP P, const Ctx& c) {
;     ...
;                 *(u32x2*)(O + (size_t)seq_row(b, dir, ck * 64 + i_) * 4096 + h * 512 + dvs * 128 + 16 * w + 4 * q4) = (u32x2){cvt_pk_bf16(a[0], a[1]), cvt_pk_bf16(a[2], a[3])}; }
;             if (has_next) RET_STORE_K(pkn);
; #pragma unroll
;             for (int dt = 0; dt < 16; ++dt) { if ((dt & 1) == 0) asm volatile("" ::: "memory");
;                 f32x4 u = Racc[dt] * gamma;
; #pragma unroll
;                 for (int ks = 0; ks < 2; ++ks) u = __builtin_amdgcn_mfma_f32_16x16x32_bf16(frag16(L + OFF_KT + (16 * dt + r16) * TP + (32 * ks + 8 * q4) * 2), frag16(vtp + 64 * ks), u, 0, 0, 0);
;                 Racc[dt] = u * g63; }
.LBB0_2553:
	v_ashrrev_i32_e32 v47, 31, v46
	s_nop 3
	v_cvt_pk_bf16_f32 v42, v42, v43
	v_cvt_pk_bf16_f32 v43, v44, v45
	v_lshlrev_b64 v[44:45], 13, v[46:47]
	v_lshl_add_u64 v[44:45], v[156:157], 0, v[44:45]
	global_store_dwordx2 v[44:45], v[42:43], off
	s_waitcnt vmcnt(7)
	ds_write_b128 v149, v[26:29] offset:33792
	s_waitcnt vmcnt(6)
	ds_write_b128 v151, v[30:33] offset:33792
	s_waitcnt vmcnt(5)
	ds_write_b128 v197, v[34:37] offset:33792
	s_waitcnt vmcnt(4)
	ds_write_b128 v198, v[38:41] offset:33792
	v_add3_u32 v26, s76, v200, v201
	ds_read_b128 v[48:51], v196
	ds_read_b128 v[52:55], v196 offset:64
	ds_read_b128 v[56:59], v26 offset:0
	ds_read_b128 v[60:63], v26 offset:64
	ds_read_b128 v[64:67], v26 offset:2304
	ds_read_b128 v[68:71], v26 offset:2368
	ds_read_b128 v[204:207], v26 offset:4608
	ds_read_b128 v[208:211], v26 offset:4672
	ds_read_b128 v[212:215], v26 offset:6912
	ds_read_b128 v[216:219], v26 offset:6976
	v_mov_b32_e32 v149, v148
	v_mov_b32_e32 v151, v150
	v_pk_mul_f32 v[30:31], v[148:149], v[146:147]
	v_pk_mul_f32 v[28:29], v[152:153], v[144:145]
	s_waitcnt lgkmcnt(6)
	s_nop 0
	v_mfma_f32_16x16x32_bf16 v[28:31], v[56:59], v[48:51], v[28:31]
	v_mfma_f32_16x16x32_bf16 v[28:31], v[60:63], v[52:55], v[28:31]
	ds_read_b128 v[220:223], v26 offset:9216
	ds_read_b128 v[224:227], v26 offset:9280
	v_pk_mul_f32 v[34:35], v[148:149], v[106:107]
	v_pk_mul_f32 v[32:33], v[152:153], v[104:105]
	s_waitcnt lgkmcnt(6)
	s_nop 0
	v_mfma_f32_16x16x32_bf16 v[32:35], v[64:67], v[48:51], v[32:35]
	v_mfma_f32_16x16x32_bf16 v[32:35], v[68:71], v[52:55], v[32:35]
	ds_read_b128 v[56:59], v26 offset:11520
	ds_read_b128 v[60:63], v26 offset:11584
	v_pk_mul_f32 v[146:147], v[150:151], v[30:31]
	v_pk_mul_f32 v[144:145], v[154:155], v[28:29]
	v_pk_mul_f32 v[30:31], v[148:149], v[126:127]
	v_pk_mul_f32 v[28:29], v[152:153], v[124:125]
	s_waitcnt lgkmcnt(6)
	s_nop 0
	v_mfma_f32_16x16x32_bf16 v[28:31], v[204:207], v[48:51], v[28:31]
	v_mfma_f32_16x16x32_bf16 v[28:31], v[208:211], v[52:55], v[28:31]
	ds_read_b128 v[64:67], v26 offset:13824
	ds_read_b128 v[68:71], v26 offset:13888
	v_pk_mul_f32 v[106:107], v[150:151], v[34:35]
	v_pk_mul_f32 v[104:105], v[154:155], v[32:33]
	v_pk_mul_f32 v[34:35], v[148:149], v[90:91]
	v_pk_mul_f32 v[32:33], v[152:153], v[88:89]
	s_waitcnt lgkmcnt(6)
	s_nop 0
	v_mfma_f32_16x16x32_bf16 v[32:35], v[212:215], v[48:51], v[32:35]
	v_mfma_f32_16x16x32_bf16 v[32:35], v[216:219], v[52:55], v[32:35]
	ds_read_b128 v[204:207], v26 offset:16128
	ds_read_b128 v[208:211], v26 offset:16192
	v_pk_mul_f32 v[126:127], v[150:151], v[30:31]
	v_pk_mul_f32 v[124:125], v[154:155], v[28:29]
	v_pk_mul_f32 v[30:31], v[148:149], v[118:119]
	v_pk_mul_f32 v[28:29], v[152:153], v[116:117]
	s_waitcnt lgkmcnt(6)
	s_nop 0
	v_mfma_f32_16x16x32_bf16 v[28:31], v[220:223], v[48:51], v[28:31]
	v_mfma_f32_16x16x32_bf16 v[28:31], v[224:227], v[52:55], v[28:31]
	ds_read_b128 v[212:215], v26 offset:18432
	ds_read_b128 v[216:219], v26 offset:18496
	v_pk_mul_f32 v[90:91], v[150:151], v[34:35]
	v_pk_mul_f32 v[88:89], v[154:155], v[32:33]
	v_pk_mul_f32 v[34:35], v[148:149], v[142:143]
	v_pk_mul_f32 v[32:33], v[152:153], v[140:141]
	s_waitcnt lgkmcnt(6)
	s_nop 0
	v_mfma_f32_16x16x32_bf16 v[32:35], v[56:59], v[48:51], v[32:35]
	v_mfma_f32_16x16x32_bf16 v[32:35], v[60:63], v[52:55], v[32:35]
	ds_read_b128 v[220:223], v26 offset:20736
	ds_read_b128 v[224:227], v26 offset:20800
	v_pk_mul_f32 v[118:119], v[150:151], v[30:31]
	v_pk_mul_f32 v[116:117], v[154:155], v[28:29]
	v_pk_mul_f32 v[30:31], v[148:149], v[110:111]
	v_pk_mul_f32 v[28:29], v[152:153], v[108:109]
	s_waitcnt lgkmcnt(6)
	s_nop 0
	v_mfma_f32_16x16x32_bf16 v[28:31], v[64:67], v[48:51], v[28:31]
	v_mfma_f32_16x16x32_bf16 v[28:31], v[68:71], v[52:55], v[28:31]
	ds_read_b128 v[56:59], v26 offset:23040
	ds_read_b128 v[60:63], v26 offset:23104
	v_pk_mul_f32 v[142:143], v[150:151], v[34:35]
	v_pk_mul_f32 v[140:141], v[154:155], v[32:33]
	v_pk_mul_f32 v[34:35], v[148:149], v[134:135]
	v_pk_mul_f32 v[32:33], v[152:153], v[132:133]
	s_waitcnt lgkmcnt(6)
; __device__ __forceinline__ void phase_ret_scan(KP P, const Ctx& c) {
;     ...
;             for (int dt = 0; dt < 16; ++dt) { if ((dt & 1) == 0) asm volatile("" ::: "memory");
;                 f32x4 u = Racc[dt] * gamma;
; #pragma unroll
;                 for (int ks = 0; ks < 2; ++ks) u = __builtin_amdgcn_mfma_f32_16x16x32_bf16(frag16(L + OFF_KT + (16 * dt + r16) * TP + (32 * ks + 8 * q4) * 2), frag16(vtp + 64 * ks), u, 0, 0, 0);
;                 Racc[dt] = u * g63; }
	s_nop 0
	v_mfma_f32_16x16x32_bf16 v[32:35], v[204:207], v[48:51], v[32:35]
	v_mfma_f32_16x16x32_bf16 v[32:35], v[208:211], v[52:55], v[32:35]
	ds_read_b128 v[64:67], v26 offset:25344
	ds_read_b128 v[68:71], v26 offset:25408
	v_pk_mul_f32 v[110:111], v[150:151], v[30:31]
	v_pk_mul_f32 v[108:109], v[154:155], v[28:29]
	v_pk_mul_f32 v[30:31], v[148:149], v[102:103]
	v_pk_mul_f32 v[28:29], v[152:153], v[100:101]
	s_waitcnt lgkmcnt(6)
	s_nop 0
	v_mfma_f32_16x16x32_bf16 v[28:31], v[212:215], v[48:51], v[28:31]
	v_mfma_f32_16x16x32_bf16 v[28:31], v[216:219], v[52:55], v[28:31]
	ds_read_b128 v[204:207], v26 offset:27648
	ds_read_b128 v[208:211], v26 offset:27712
	v_pk_mul_f32 v[134:135], v[150:151], v[34:35]
	v_pk_mul_f32 v[132:133], v[154:155], v[32:33]
	v_pk_mul_f32 v[34:35], v[148:149], v[130:131]
	v_pk_mul_f32 v[32:33], v[152:153], v[128:129]
	s_waitcnt lgkmcnt(6)
	s_nop 0
	v_mfma_f32_16x16x32_bf16 v[32:35], v[220:223], v[48:51], v[32:35]
	v_mfma_f32_16x16x32_bf16 v[32:35], v[224:227], v[52:55], v[32:35]
	ds_read_b128 v[212:215], v26 offset:29952
	ds_read_b128 v[216:219], v26 offset:30016
	v_pk_mul_f32 v[102:103], v[150:151], v[30:31]
	v_pk_mul_f32 v[100:101], v[154:155], v[28:29]
	v_pk_mul_f32 v[30:31], v[148:149], v[98:99]
	v_pk_mul_f32 v[28:29], v[152:153], v[96:97]
	s_waitcnt lgkmcnt(6)
	s_nop 0
	v_mfma_f32_16x16x32_bf16 v[28:31], v[56:59], v[48:51], v[28:31]
	v_mfma_f32_16x16x32_bf16 v[28:31], v[60:63], v[52:55], v[28:31]
	ds_read_b128 v[220:223], v26 offset:32256
	ds_read_b128 v[224:227], v26 offset:32320
	v_pk_mul_f32 v[130:131], v[150:151], v[34:35]
	v_pk_mul_f32 v[128:129], v[154:155], v[32:33]
	v_pk_mul_f32 v[34:35], v[148:149], v[122:123]
	v_pk_mul_f32 v[32:33], v[152:153], v[120:121]
	s_waitcnt lgkmcnt(6)
	s_nop 0
	v_mfma_f32_16x16x32_bf16 v[32:35], v[64:67], v[48:51], v[32:35]
	v_mfma_f32_16x16x32_bf16 v[32:35], v[68:71], v[52:55], v[32:35]
	ds_read_b128 v[56:59], v26 offset:34560
	ds_read_b128 v[60:63], v26 offset:34624
	v_pk_mul_f32 v[98:99], v[150:151], v[30:31]
	v_pk_mul_f32 v[96:97], v[154:155], v[28:29]
	v_pk_mul_f32 v[30:31], v[148:149], v[94:95]
	v_pk_mul_f32 v[28:29], v[152:153], v[92:93]
	s_waitcnt lgkmcnt(6)
	s_nop 0
	v_mfma_f32_16x16x32_bf16 v[28:31], v[204:207], v[48:51], v[28:31]
	v_mfma_f32_16x16x32_bf16 v[28:31], v[208:211], v[52:55], v[28:31]
	v_pk_mul_f32 v[122:123], v[150:151], v[34:35]
	v_pk_mul_f32 v[120:121], v[154:155], v[32:33]
	v_pk_mul_f32 v[34:35], v[148:149], v[114:115]
	v_pk_mul_f32 v[32:33], v[152:153], v[112:113]
	s_waitcnt lgkmcnt(4)
	s_nop 0
	v_mfma_f32_16x16x32_bf16 v[32:35], v[212:215], v[48:51], v[32:35]
	v_mfma_f32_16x16x32_bf16 v[32:35], v[216:219], v[52:55], v[32:35]
	v_pk_mul_f32 v[94:95], v[150:151], v[30:31]
	v_pk_mul_f32 v[92:93], v[154:155], v[28:29]
	v_pk_mul_f32 v[30:31], v[148:149], v[86:87]
	v_pk_mul_f32 v[28:29], v[152:153], v[84:85]
	s_waitcnt lgkmcnt(2)
	s_nop 0
	v_mfma_f32_16x16x32_bf16 v[28:31], v[220:223], v[48:51], v[28:31]
	v_mfma_f32_16x16x32_bf16 v[28:31], v[224:227], v[52:55], v[28:31]
	v_pk_mul_f32 v[114:115], v[150:151], v[34:35]
	v_pk_mul_f32 v[112:113], v[154:155], v[32:33]
	v_pk_mul_f32 v[34:35], v[148:149], v[138:139]
	v_pk_mul_f32 v[32:33], v[152:153], v[136:137]
	s_waitcnt lgkmcnt(0)
	s_nop 0
	v_mfma_f32_16x16x32_bf16 v[32:35], v[56:59], v[48:51], v[32:35]
	v_mfma_f32_16x16x32_bf16 v[32:35], v[60:63], v[52:55], v[32:35]
	v_pk_mul_f32 v[86:87], v[150:151], v[30:31]
	v_pk_mul_f32 v[84:85], v[154:155], v[28:29]
	s_nop 5
	v_pk_mul_f32 v[138:139], v[150:151], v[34:35]
	v_pk_mul_f32 v[136:137], v[154:155], v[32:33]
	s_add_i32 s25, s25, 64
	s_sub_i32 s24, s24, 64
	s_add_i32 s26, s26, 1
	s_cmpk_eq_i32 s25, 0x10c0
	s_cbranch_scc1 .LBB0_2551
